# fastdiv version with the in-projection GEMM loop shifted by one 4-byte pad (code placement test)
# speedup vs baseline: 1.0059x; 1.0059x over previous
; DI int TID() { int t = __builtin_amdgcn_workitem_id_x(); asm volatile("" : "+v"(t)); return t; }
; #define PG8_STAGE(bufoff, gbase, voff) do { _Pragma("unroll") for (int _i = 0; _i < 2; ++_i) \
;         __builtin_amdgcn_global_load_lds((const unsigned*)((const char*)(gbase) + (voff)[_i]), (LAS unsigned*)(lds + (bufoff) + ldsw + _i * 8192), 16, 0, 0); } while (0)
; #define PG8_WAIT_V(n) asm volatile("s_waitcnt vmcnt(" #n ")" ::: "memory")
; #define PG8_BAR __builtin_amdgcn_s_barrier()
; template <class Epi, class Sched>
; DI void gemm_phase(LAS unsigned char* lds, const Gemm g, const Sched& S, const Epi& E) {
;     const int tid = TID(), wid = __builtin_amdgcn_readfirstlane(tid >> 6), lane = tid & 63, wr = wid >> 2, wc = wid & 3, fr = lane & 15, fq = lane >> 4;
;     const int K = g.K, nt = K / BK;
;     unsigned voffA[2], voffB[2];
; #pragma unroll
;     for (int i = 0; i < 2; ++i) { int R, C; stage_rc(tid * 16 + i * 8192, R, C); const int Rb = Epi::PERM ? ((R & ~31) + perm32(R & 31)) : R;
;         voffA[i] = (unsigned)(R * g.lda + C) * 2u; voffB[i] = (unsigned)(Rb * g.ldb + C) * 2u; }
;     const size_t kstep = (size_t)(BK * 2);
;     const size_t hstepA = (size_t)HALF * g.lda * 2, hstepB = (size_t)HALF * g.ldb * 2;
;     const size_t tstepA = 2 * hstepA, tstepB = 2 * hstepB;
;     const unsigned ldsw = (unsigned)wid * 1024u;
;     const int aoff = lds_byte(wr * 64 + fr, fq * 8), boff = lds_byte(wc * 32 + fr, fq * 8);
;     ...
;     Unit cur, nxt; int ui = 0;
;     if (!S.next(0, cur)) return;
;     f32x4 acc[2][2][4][2];
; #pragma unroll
;     for (int a = 0; a < 2; ++a)
; #pragma unroll
;         for (int b = 0; b < 2; ++b)
; #pragma unroll
;             for (int m = 0; m < 4; ++m)
; #pragma unroll
;                 for (int n = 0; n < 2; ++n) acc[a][b][m][n] = (f32x4){0.f, 0.f, 0.f, 0.f};
;     bf16x8 At[4][2], B0[2][2], B1[2][2];
;     const char* cA = (const char*)g.A + (size_t)cur.pm * tstepA; const char* cB = (const char*)g.Bt + (size_t)cur.pn * tstepB;
;     PG8_STAGE(PG8_SB(0, 0), cB, voffB); PG8_STAGE(PG8_SA(0, 0), cA, voffA); PG8_STAGE(PG8_SB(0, 1), cB + hstepB, voffB); PG8_STAGE(PG8_SA(0, 1), cA + hstepA, voffA);
;     if (wr == 1) PG8_BAR;
;     PG8_WAIT_V(4); PG8_BAR;
;     PG8_STAGE(PG8_SB(1, 0), cB + kstep, voffB); PG8_STAGE(PG8_SA(1, 0), cA + kstep, voffA); PG8_STAGE(PG8_SB(1, 1), cB + hstepB + kstep, voffB);
;     PG8_WAIT_V(6); PG8_BAR;
.LBB0_1202:
	s_and_b64 s[4:5], s[28:29], exec
	s_cselect_b32 s58, 16, 32
	s_cselect_b32 s59, s30, s63
	s_add_u32 s30, s94, 0x2a100000
	s_addc_u32 s31, s95, 0
	s_add_u32 s4, s94, 0x1c100000
	s_addc_u32 s5, s95, 0
	s_add_u32 s28, s94, 0x22100000
	v_writelane_b32 v254, s28, 51
	s_addc_u32 s28, s95, 0
	v_writelane_b32 v254, s28, 49
	s_cmp_eq_u32 s34, 0
	s_mov_b32 s28, 0x2c900000
	s_cselect_b32 s28, s28, 0x2da24000
	s_add_u32 s38, s94, s28
	s_addc_u32 s39, s95, 0
	s_and_b32 s34, s35, 3
	s_add_i32 m0, s25, 0x18000
	v_lshl_add_u64 v[10:11], v[10:11], 0, s[78:79]
	s_lshl_b32 s64, s36, 6
	s_lshl_b32 s35, s36, 13
	s_lshl_b32 s36, s34, 12
	s_waitcnt vmcnt(4)
	s_barrier
	global_load_lds_dwordx4 v[10:11], off
	v_lshl_add_u64 v[8:9], v[8:9], 0, s[78:79]
	s_add_i32 m0, s25, 0x1a000
	s_add_i32 s65, s25, 0x8000
	s_add_i32 s82, s25, 0xa000
	global_load_lds_dwordx4 v[8:9], off
	v_lshl_add_u64 v[6:7], v[6:7], 0, s[78:79]
	s_mov_b32 m0, s65
	s_add_u32 s28, s2, 0x80080
	global_load_lds_dwordx4 v[6:7], off
	v_lshl_add_u64 v[4:5], v[4:5], 0, s[78:79]
	s_mov_b32 m0, s82
	s_addc_u32 s29, s3, 0
	global_load_lds_dwordx4 v[4:5], off
	s_add_i32 m0, s25, 0x1c000
	v_lshl_add_u64 v[4:5], s[28:29], 0, v[132:133]
	global_load_lds_dwordx4 v[4:5], off
	v_lshl_add_u64 v[4:5], s[28:29], 0, v[136:137]
	s_add_i32 m0, s25, 0x1e000
	v_and_b32_e32 v6, 15, v2
	global_load_lds_dwordx4 v[4:5], off
	v_bfe_u32 v5, v2, 4, 2
	v_lshlrev_b32_e32 v4, 3, v5
	v_lshlrev_b32_e32 v10, 4, v5
	v_lshlrev_b32_e32 v2, 2, v2
	v_lshl_or_b32 v7, v6, 6, v10
	v_and_b32_e32 v2, 32, v2
	v_lshl_or_b32 v138, s34, 5, v4
	v_bitop3_b32 v11, v7, s35, v2 bitop3:0xde
	v_bitop3_b32 v156, v7, s36, v2 bitop3:0xde
	v_lshlrev_b32_e32 v2, 5, v138
	v_or_b32_e32 v139, s64, v6
	v_and_b32_e32 v157, 0xe00, v2
	v_lshlrev_b32_e32 v6, 5, v6
	v_lshlrev_b32_e32 v2, 5, v5
	v_mov_b32_e32 v7, v3
	v_lshl_add_u64 v[140:141], s[38:39], 0, v[2:3]
	v_lshl_add_u64 v[8:9], s[30:31], 0, v[6:7]
	v_and_b32_e32 v2, 16, v10
	v_lshl_add_u64 v[142:143], v[8:9], 0, v[2:3]
	v_lshl_add_u64 v[8:9], s[30:31], 0, v[2:3]
	v_or_b32_e32 v2, 0x200, v6
	v_lshl_add_u64 v[144:145], v[8:9], 0, v[2:3]
	v_lshlrev_b32_e32 v2, 15, v12
	v_and_b32_e32 v2, 0xffff0000, v2
	v_cmp_gt_u32_e32 vcc, 2, v5
	v_lshl_add_u32 v2, v13, 12, v2
	v_and_b32_e32 v5, 1, v12
	s_add_i32 s84, s58, -2
	v_lshl_or_b32 v2, v5, 6, v2
	s_cmp_eq_u32 s34, 0
	v_lshl_add_u32 v146, v14, 1, v2
	v_lshlrev_b32_e32 v2, 15, v15
	s_cselect_b64 s[28:29], -1, 0
	v_and_b32_e32 v2, 0xffff0000, v2
	s_waitcnt vmcnt(6)
	s_and_b64 s[28:29], s[28:29], vcc
	s_ashr_i32 s85, s59, 31
	v_lshl_add_u32 v2, v16, 12, v2
	v_and_b32_e32 v5, 1, v15
	v_or_b32_e32 v4, 0x80, v138
	s_cmp_gt_i32 s59, -1
	v_lshl_or_b32 v2, v5, 6, v2
	s_mov_b32 s83, 0
	v_writelane_b32 v254, s28, 57
	v_or_b32_e32 v158, 0x1000, v157
	s_cselect_b64 s[30:31], -1, 0
	v_mov_b32_e32 v147, v3
	v_lshl_add_u32 v148, v17, 1, v2
	v_mov_b32_e32 v149, v3
	v_add_u32_e32 v159, 0, v11
	v_lshlrev_b32_e32 v150, 1, v4
	s_barrier
	v_writelane_b32 v254, s29, 58
	s_branch .LBB0_1204
	s_nop 0
